# attention stage write moved from after the 1st to after the 9th PV MFMA (more flight time for the prefetched K/V tile)
# baseline (speedup 1.0000x reference)
.La1t0_nl3:
	s_waitcnt lgkmcnt(7)
	v_mfma_f32_32x32x16_bf16 v[80:95], v[156:159], v[222:225], v[194:209]
	s_nop 11
	v_exp_f32_e32 v64, v64
	v_exp_f32_e32 v65, v65
	v_exp_f32_e32 v66, v66
	v_exp_f32_e32 v67, v67
	v_exp_f32_e32 v68, v68
	v_exp_f32_e32 v69, v69
	s_waitcnt lgkmcnt(6)
	v_mfma_f32_32x32x16_bf16 v[80:95], v[152:155], v[218:221], v[80:95]
	v_exp_f32_e32 v70, v70
	v_exp_f32_e32 v71, v71
	v_exp_f32_e32 v72, v72
	v_exp_f32_e32 v73, v73
	v_exp_f32_e32 v74, v74
	v_exp_f32_e32 v75, v75
	s_waitcnt lgkmcnt(5)
	v_mfma_f32_32x32x16_bf16 v[80:95], v[148:151], v[214:217], v[80:95]
	v_exp_f32_e32 v76, v76
	v_exp_f32_e32 v77, v77
	v_exp_f32_e32 v78, v78
	v_exp_f32_e32 v79, v79
	v_cvt_pk_bf16_f32 v160, v64, v65
	v_cvt_pk_bf16_f32 v161, v66, v67
	s_waitcnt lgkmcnt(4)
	v_mfma_f32_32x32x16_bf16 v[80:95], v[144:147], v[210:213], v[80:95]
	ds_read_b128 v[144:147], v243 offset:34816
	ds_read_b128 v[148:151], v243 offset:34848
	ds_read_b128 v[152:155], v243 offset:39424
	ds_read_b128 v[156:159], v243 offset:39456
	v_cvt_pk_bf16_f32 v162, v68, v69
	v_cvt_pk_bf16_f32 v163, v70, v71
	v_cvt_pk_bf16_f32 v164, v72, v73
	v_cvt_pk_bf16_f32 v165, v74, v75
	v_cvt_pk_bf16_f32 v166, v76, v77
	v_cvt_pk_bf16_f32 v167, v78, v79
	s_nop 4
	v_exp_f32_e32 v80, v80
	v_exp_f32_e32 v81, v81
	v_exp_f32_e32 v82, v82
	v_exp_f32_e32 v83, v83
	s_waitcnt lgkmcnt(7)
	v_mfma_f32_32x32x16_bf16 v[16:31], v[128:131], v[160:163], v[16:31]
	v_exp_f32_e32 v84, v84
	v_exp_f32_e32 v85, v85
	v_exp_f32_e32 v86, v86
	s_waitcnt lgkmcnt(6)
	v_mfma_f32_32x32x16_bf16 v[16:31], v[132:135], v[164:167], v[16:31]
	ds_read_b128 v[128:131], v243 offset:44096
	ds_read_b128 v[132:135], v243 offset:44128
	v_exp_f32_e32 v87, v87
	v_exp_f32_e32 v88, v88
	v_exp_f32_e32 v89, v89
	s_waitcnt lgkmcnt(7)
	v_mfma_f32_32x32x16_bf16 v[0:15], v[136:139], v[160:163], v[0:15]
	v_exp_f32_e32 v90, v90
	v_exp_f32_e32 v91, v91
	v_exp_f32_e32 v92, v92
	s_waitcnt lgkmcnt(6)
	v_mfma_f32_32x32x16_bf16 v[0:15], v[140:143], v[164:167], v[0:15]
	ds_read_b128 v[136:139], v243 offset:48704
	ds_read_b128 v[140:143], v243 offset:48736
	v_exp_f32_e32 v93, v93
	v_exp_f32_e32 v94, v94
	v_exp_f32_e32 v95, v95
	s_waitcnt lgkmcnt(7)
	v_mfma_f32_32x32x16_bf16 v[48:63], v[144:147], v[160:163], v[48:63]
	v_cvt_pk_bf16_f32 v168, v80, v81
	v_cvt_pk_bf16_f32 v169, v82, v83
	s_waitcnt lgkmcnt(6)
	v_mfma_f32_32x32x16_bf16 v[48:63], v[148:151], v[164:167], v[48:63]
	ds_read_b128 v[144:147], v243 offset:34880
	ds_read_b128 v[148:151], v243 offset:34912
	v_cvt_pk_bf16_f32 v170, v84, v85
	v_cvt_pk_bf16_f32 v171, v86, v87
	s_waitcnt lgkmcnt(7)
	v_mfma_f32_32x32x16_bf16 v[32:47], v[152:155], v[160:163], v[32:47]
	v_cvt_pk_bf16_f32 v172, v88, v89
	v_cvt_pk_bf16_f32 v173, v90, v91
	s_waitcnt lgkmcnt(6)
	v_mfma_f32_32x32x16_bf16 v[32:47], v[156:159], v[164:167], v[32:47]
	ds_read_b128 v[152:155], v243 offset:39488
	ds_read_b128 v[156:159], v243 offset:39520
	v_cvt_pk_bf16_f32 v174, v92, v93
	v_cvt_pk_bf16_f32 v175, v94, v95
	s_nop 1
	s_waitcnt lgkmcnt(7)
	v_mfma_f32_32x32x16_bf16 v[16:31], v[128:131], v[168:171], v[16:31]
	s_cmp_eq_u64 s[40:41], 0
	s_cbranch_scc1 .La1t0_lv_a
	s_waitcnt vmcnt(4)
	s_branch .La1t0_lv_b

.La1t0_lv_b:
	v_add_u32_e32 v251, 0xd000, v240
	ds_write_b128 v239, v[104:107] offset:17408
	ds_write_b128 v239, v[108:111] offset:26112
	ds_write2_b64 v251, v[112:113], v[114:115] offset1:2
	v_add_u32_e32 v251, 0xf000, v240
	ds_write2_b64 v251, v[116:117], v[118:119] offset0:128 offset1:130
	v_add_f32_e32 v186, v64, v67
	v_add_f32_e32 v187, v65, v68
	v_add_f32_e32 v251, v66, v69
	v_add_f32_e32 v186, v186, v70
	v_add_f32_e32 v187, v187, v71
	s_waitcnt lgkmcnt(6)
	v_mfma_f32_32x32x16_bf16 v[16:31], v[132:135], v[172:175], v[16:31]
	v_add_f32_e32 v251, v251, v72
	v_add_f32_e32 v186, v186, v73
	v_add_f32_e32 v187, v187, v74
	v_add_f32_e32 v251, v251, v75
	v_add_f32_e32 v186, v186, v76
	s_waitcnt lgkmcnt(5)
	v_mfma_f32_32x32x16_bf16 v[0:15], v[136:139], v[168:171], v[0:15]
	v_add_f32_e32 v187, v187, v77
	v_add_f32_e32 v251, v251, v78
	v_add_f32_e32 v186, v186, v79
	v_add_f32_e32 v187, v187, v80
	v_add_f32_e32 v251, v251, v81
	s_waitcnt lgkmcnt(4)
	v_mfma_f32_32x32x16_bf16 v[0:15], v[140:143], v[172:175], v[0:15]
	v_add_f32_e32 v186, v186, v82
	v_add_f32_e32 v187, v187, v83
	v_add_f32_e32 v251, v251, v84
	v_add_f32_e32 v186, v186, v85
	v_add_f32_e32 v187, v187, v86
	s_waitcnt lgkmcnt(3)
	v_mfma_f32_32x32x16_bf16 v[48:63], v[144:147], v[168:171], v[48:63]
	v_add_f32_e32 v251, v251, v87
	v_add_f32_e32 v186, v186, v88
	v_add_f32_e32 v187, v187, v89
	v_add_f32_e32 v251, v251, v90
	v_add_f32_e32 v186, v186, v91
	s_waitcnt lgkmcnt(2)
	v_mfma_f32_32x32x16_bf16 v[48:63], v[148:151], v[172:175], v[48:63]
	v_add_f32_e32 v187, v187, v92
	v_add_f32_e32 v251, v251, v93
	v_add_f32_e32 v186, v186, v94
	v_add_f32_e32 v187, v187, v95
	v_add_f32_e32 v186, v186, v187
	s_waitcnt lgkmcnt(1)
	v_mfma_f32_32x32x16_bf16 v[32:47], v[152:155], v[168:171], v[32:47]
	v_add_f32_e32 v186, v186, v251
	v_add_f32_e32 v248, v248, v186
	s_waitcnt lgkmcnt(0)
	v_mfma_f32_32x32x16_bf16 v[32:47], v[156:159], v[172:175], v[32:47]
	s_setprio 0
	s_branch .La1t0_pw

.La1t0n_nl3:
	v_mfma_f32_32x32x16_bf16 v[80:95], v[156:159], v[222:225], v[80:95]
	s_nop 11
	v_exp_f32_e32 v64, v64
	v_exp_f32_e32 v65, v65
	v_exp_f32_e32 v66, v66
	v_exp_f32_e32 v67, v67
	v_exp_f32_e32 v68, v68
	v_exp_f32_e32 v69, v69
	v_mfma_f32_32x32x16_bf16 v[80:95], v[152:155], v[218:221], v[80:95]
	v_exp_f32_e32 v70, v70
	v_exp_f32_e32 v71, v71
	v_exp_f32_e32 v72, v72
	v_exp_f32_e32 v73, v73
	v_exp_f32_e32 v74, v74
	v_exp_f32_e32 v75, v75
	v_mfma_f32_32x32x16_bf16 v[80:95], v[148:151], v[214:217], v[80:95]
	v_exp_f32_e32 v76, v76
	v_exp_f32_e32 v77, v77
	v_exp_f32_e32 v78, v78
	v_exp_f32_e32 v79, v79
	v_cvt_pk_bf16_f32 v160, v64, v65
	v_cvt_pk_bf16_f32 v161, v66, v67
	v_mfma_f32_32x32x16_bf16 v[80:95], v[144:147], v[210:213], v[80:95]
	ds_read_b128 v[144:147], v243 offset:34816
	ds_read_b128 v[148:151], v243 offset:34848
	ds_read_b128 v[152:155], v243 offset:39424
	ds_read_b128 v[156:159], v243 offset:39456
	v_cvt_pk_bf16_f32 v162, v68, v69
	v_cvt_pk_bf16_f32 v163, v70, v71
	v_cvt_pk_bf16_f32 v164, v72, v73
	v_cvt_pk_bf16_f32 v165, v74, v75
	v_cvt_pk_bf16_f32 v166, v76, v77
	v_cvt_pk_bf16_f32 v167, v78, v79
	s_nop 4
	v_exp_f32_e32 v80, v80
	v_exp_f32_e32 v81, v81
	v_exp_f32_e32 v82, v82
	v_exp_f32_e32 v83, v83
	s_waitcnt lgkmcnt(7)
	v_mfma_f32_32x32x16_bf16 v[16:31], v[128:131], v[160:163], v[16:31]
	v_exp_f32_e32 v84, v84
	v_exp_f32_e32 v85, v85
	v_exp_f32_e32 v86, v86
	s_waitcnt lgkmcnt(6)
	v_mfma_f32_32x32x16_bf16 v[16:31], v[132:135], v[164:167], v[16:31]
	ds_read_b128 v[128:131], v243 offset:44096
	ds_read_b128 v[132:135], v243 offset:44128
	v_exp_f32_e32 v87, v87
	v_exp_f32_e32 v88, v88
	v_exp_f32_e32 v89, v89
	s_waitcnt lgkmcnt(7)
	v_mfma_f32_32x32x16_bf16 v[0:15], v[136:139], v[160:163], v[0:15]
	v_exp_f32_e32 v90, v90
	v_exp_f32_e32 v91, v91
	v_exp_f32_e32 v92, v92
	s_waitcnt lgkmcnt(6)
	v_mfma_f32_32x32x16_bf16 v[0:15], v[140:143], v[164:167], v[0:15]
	ds_read_b128 v[136:139], v243 offset:48704
	ds_read_b128 v[140:143], v243 offset:48736
	v_exp_f32_e32 v93, v93
	v_exp_f32_e32 v94, v94
	v_exp_f32_e32 v95, v95
	s_waitcnt lgkmcnt(7)
	v_mfma_f32_32x32x16_bf16 v[48:63], v[144:147], v[160:163], v[48:63]
	v_cvt_pk_bf16_f32 v168, v80, v81
	v_cvt_pk_bf16_f32 v169, v82, v83
	s_waitcnt lgkmcnt(6)
	v_mfma_f32_32x32x16_bf16 v[48:63], v[148:151], v[164:167], v[48:63]
	ds_read_b128 v[144:147], v243 offset:34880
	ds_read_b128 v[148:151], v243 offset:34912
	v_cvt_pk_bf16_f32 v170, v84, v85
	v_cvt_pk_bf16_f32 v171, v86, v87
	s_waitcnt lgkmcnt(7)
	v_mfma_f32_32x32x16_bf16 v[32:47], v[152:155], v[160:163], v[32:47]
	v_cvt_pk_bf16_f32 v172, v88, v89
	v_cvt_pk_bf16_f32 v173, v90, v91
	s_waitcnt lgkmcnt(6)
	v_mfma_f32_32x32x16_bf16 v[32:47], v[156:159], v[164:167], v[32:47]
	ds_read_b128 v[152:155], v243 offset:39488
	ds_read_b128 v[156:159], v243 offset:39520
	v_cvt_pk_bf16_f32 v174, v92, v93
	v_cvt_pk_bf16_f32 v175, v94, v95
	s_nop 1
	s_waitcnt lgkmcnt(7)
	v_mfma_f32_32x32x16_bf16 v[16:31], v[128:131], v[168:171], v[16:31]
	s_cmp_eq_u64 s[40:41], 0
	s_cbranch_scc1 .La1t0n_lv_a
	s_waitcnt vmcnt(4)
	s_branch .La1t0n_lv_b

.La1t1_nl3:
	s_waitcnt lgkmcnt(7)
	v_mfma_f32_32x32x16_bf16 v[80:95], v[156:159], v[222:225], v[194:209]
	s_nop 11
	v_exp_f32_e32 v64, v64
	v_exp_f32_e32 v65, v65
	v_exp_f32_e32 v66, v66
	v_exp_f32_e32 v67, v67
	v_exp_f32_e32 v68, v68
	v_exp_f32_e32 v69, v69
	s_waitcnt lgkmcnt(6)
	v_mfma_f32_32x32x16_bf16 v[80:95], v[152:155], v[218:221], v[80:95]
	v_exp_f32_e32 v70, v70
	v_exp_f32_e32 v71, v71
	v_exp_f32_e32 v72, v72
	v_exp_f32_e32 v73, v73
	v_exp_f32_e32 v74, v74
	v_exp_f32_e32 v75, v75
	s_waitcnt lgkmcnt(5)
	v_mfma_f32_32x32x16_bf16 v[80:95], v[148:151], v[214:217], v[80:95]
	v_exp_f32_e32 v76, v76
	v_exp_f32_e32 v77, v77
	v_exp_f32_e32 v78, v78
	v_exp_f32_e32 v79, v79
	v_cvt_pk_bf16_f32 v160, v64, v65
	v_cvt_pk_bf16_f32 v161, v66, v67
	s_waitcnt lgkmcnt(4)
	v_mfma_f32_32x32x16_bf16 v[80:95], v[144:147], v[210:213], v[80:95]
	ds_read_b128 v[144:147], v243 offset:53248
	ds_read_b128 v[148:151], v243 offset:53280
	ds_read_b128 v[152:155], v243 offset:57856
	ds_read_b128 v[156:159], v243 offset:57888
	v_cvt_pk_bf16_f32 v162, v68, v69
	v_cvt_pk_bf16_f32 v163, v70, v71
	v_cvt_pk_bf16_f32 v164, v72, v73
	v_cvt_pk_bf16_f32 v165, v74, v75
	v_cvt_pk_bf16_f32 v166, v76, v77
	v_cvt_pk_bf16_f32 v167, v78, v79
	s_nop 4
	v_exp_f32_e32 v80, v80
	v_exp_f32_e32 v81, v81
	v_exp_f32_e32 v82, v82
	v_exp_f32_e32 v83, v83
	s_waitcnt lgkmcnt(7)
	v_mfma_f32_32x32x16_bf16 v[16:31], v[128:131], v[160:163], v[16:31]
	v_exp_f32_e32 v84, v84
	v_exp_f32_e32 v85, v85
	v_exp_f32_e32 v86, v86
	s_waitcnt lgkmcnt(6)
	v_mfma_f32_32x32x16_bf16 v[16:31], v[132:135], v[164:167], v[16:31]
	ds_read_b128 v[128:131], v243 offset:62528
	ds_read_b128 v[132:135], v243 offset:62560
	v_exp_f32_e32 v87, v87
	v_exp_f32_e32 v88, v88
	v_exp_f32_e32 v89, v89
	s_waitcnt lgkmcnt(7)
	v_mfma_f32_32x32x16_bf16 v[0:15], v[136:139], v[160:163], v[0:15]
	v_exp_f32_e32 v90, v90
	v_exp_f32_e32 v91, v91
	v_exp_f32_e32 v92, v92
	s_waitcnt lgkmcnt(6)
	v_mfma_f32_32x32x16_bf16 v[0:15], v[140:143], v[164:167], v[0:15]
	ds_read_b128 v[136:139], v244 offset:13888
	ds_read_b128 v[140:143], v244 offset:13920
	v_exp_f32_e32 v93, v93
	v_exp_f32_e32 v94, v94
	v_exp_f32_e32 v95, v95
	s_waitcnt lgkmcnt(7)
	v_mfma_f32_32x32x16_bf16 v[48:63], v[144:147], v[160:163], v[48:63]
	v_cvt_pk_bf16_f32 v168, v80, v81
	v_cvt_pk_bf16_f32 v169, v82, v83
	s_waitcnt lgkmcnt(6)
	v_mfma_f32_32x32x16_bf16 v[48:63], v[148:151], v[164:167], v[48:63]
	ds_read_b128 v[144:147], v243 offset:53312
	ds_read_b128 v[148:151], v243 offset:53344
	v_cvt_pk_bf16_f32 v170, v84, v85
	v_cvt_pk_bf16_f32 v171, v86, v87
	s_waitcnt lgkmcnt(7)
	v_mfma_f32_32x32x16_bf16 v[32:47], v[152:155], v[160:163], v[32:47]
	v_cvt_pk_bf16_f32 v172, v88, v89
	v_cvt_pk_bf16_f32 v173, v90, v91
	s_waitcnt lgkmcnt(6)
	v_mfma_f32_32x32x16_bf16 v[32:47], v[156:159], v[164:167], v[32:47]
	ds_read_b128 v[152:155], v243 offset:57920
	ds_read_b128 v[156:159], v243 offset:57952
	v_cvt_pk_bf16_f32 v174, v92, v93
	v_cvt_pk_bf16_f32 v175, v94, v95
	s_nop 1
	s_waitcnt lgkmcnt(7)
	v_mfma_f32_32x32x16_bf16 v[16:31], v[128:131], v[168:171], v[16:31]
	s_cmp_eq_u64 s[40:41], 0
	s_cbranch_scc1 .La1t1_lv_s
	s_waitcnt vmcnt(4)
	ds_write_b128 v239, v[96:99]
	ds_write_b128 v239, v[100:103] offset:8704
	ds_write2_b64 v241, v[120:121], v[122:123] offset1:2
	ds_write2_b64 v242, v[124:125], v[126:127] offset0:128 offset1:130
.La1t1_lv_s:
	v_add_f32_e32 v186, v64, v67
	v_add_f32_e32 v187, v65, v68
	v_add_f32_e32 v251, v66, v69
	v_add_f32_e32 v186, v186, v70
	v_add_f32_e32 v187, v187, v71
	s_waitcnt lgkmcnt(6)
	v_mfma_f32_32x32x16_bf16 v[16:31], v[132:135], v[172:175], v[16:31]
	v_add_f32_e32 v251, v251, v72
	v_add_f32_e32 v186, v186, v73
	v_add_f32_e32 v187, v187, v74
	v_add_f32_e32 v251, v251, v75
	v_add_f32_e32 v186, v186, v76
	s_waitcnt lgkmcnt(5)
	v_mfma_f32_32x32x16_bf16 v[0:15], v[136:139], v[168:171], v[0:15]
	v_add_f32_e32 v187, v187, v77
	v_add_f32_e32 v251, v251, v78
	v_add_f32_e32 v186, v186, v79
	v_add_f32_e32 v187, v187, v80
	v_add_f32_e32 v251, v251, v81
	s_waitcnt lgkmcnt(4)
	v_mfma_f32_32x32x16_bf16 v[0:15], v[140:143], v[172:175], v[0:15]
	v_add_f32_e32 v186, v186, v82
	v_add_f32_e32 v187, v187, v83
	v_add_f32_e32 v251, v251, v84
	v_add_f32_e32 v186, v186, v85
	v_add_f32_e32 v187, v187, v86
	s_waitcnt lgkmcnt(3)
	v_mfma_f32_32x32x16_bf16 v[48:63], v[144:147], v[168:171], v[48:63]
	v_add_f32_e32 v251, v251, v87
	v_add_f32_e32 v186, v186, v88
	v_add_f32_e32 v187, v187, v89
	v_add_f32_e32 v251, v251, v90
	v_add_f32_e32 v186, v186, v91
	s_waitcnt lgkmcnt(2)
	v_mfma_f32_32x32x16_bf16 v[48:63], v[148:151], v[172:175], v[48:63]
	v_add_f32_e32 v187, v187, v92
	v_add_f32_e32 v251, v251, v93
	v_add_f32_e32 v186, v186, v94
	v_add_f32_e32 v187, v187, v95
	v_add_f32_e32 v186, v186, v187
	s_waitcnt lgkmcnt(1)
	v_mfma_f32_32x32x16_bf16 v[32:47], v[152:155], v[168:171], v[32:47]
	v_add_f32_e32 v186, v186, v251
	v_add_f32_e32 v248, v248, v186
	s_waitcnt lgkmcnt(0)
	v_mfma_f32_32x32x16_bf16 v[32:47], v[156:159], v[172:175], v[32:47]
	s_setprio 0
	s_branch .LBB0_583

.La1t1n_nl3:
	v_mfma_f32_32x32x16_bf16 v[80:95], v[156:159], v[222:225], v[80:95]
	s_nop 11
	v_exp_f32_e32 v64, v64
	v_exp_f32_e32 v65, v65
	v_exp_f32_e32 v66, v66
	v_exp_f32_e32 v67, v67
	v_exp_f32_e32 v68, v68
	v_exp_f32_e32 v69, v69
	v_mfma_f32_32x32x16_bf16 v[80:95], v[152:155], v[218:221], v[80:95]
	v_exp_f32_e32 v70, v70
	v_exp_f32_e32 v71, v71
	v_exp_f32_e32 v72, v72
	v_exp_f32_e32 v73, v73
	v_exp_f32_e32 v74, v74
	v_exp_f32_e32 v75, v75
	v_mfma_f32_32x32x16_bf16 v[80:95], v[148:151], v[214:217], v[80:95]
	v_exp_f32_e32 v76, v76
	v_exp_f32_e32 v77, v77
	v_exp_f32_e32 v78, v78
	v_exp_f32_e32 v79, v79
	v_cvt_pk_bf16_f32 v160, v64, v65
	v_cvt_pk_bf16_f32 v161, v66, v67
	v_mfma_f32_32x32x16_bf16 v[80:95], v[144:147], v[210:213], v[80:95]
	ds_read_b128 v[144:147], v243 offset:53248
	ds_read_b128 v[148:151], v243 offset:53280
	ds_read_b128 v[152:155], v243 offset:57856
	ds_read_b128 v[156:159], v243 offset:57888
	v_cvt_pk_bf16_f32 v162, v68, v69
	v_cvt_pk_bf16_f32 v163, v70, v71
	v_cvt_pk_bf16_f32 v164, v72, v73
	v_cvt_pk_bf16_f32 v165, v74, v75
	v_cvt_pk_bf16_f32 v166, v76, v77
	v_cvt_pk_bf16_f32 v167, v78, v79
	s_nop 4
	v_exp_f32_e32 v80, v80
	v_exp_f32_e32 v81, v81
	v_exp_f32_e32 v82, v82
	v_exp_f32_e32 v83, v83
	s_waitcnt lgkmcnt(7)
	v_mfma_f32_32x32x16_bf16 v[16:31], v[128:131], v[160:163], v[16:31]
	v_exp_f32_e32 v84, v84
	v_exp_f32_e32 v85, v85
	v_exp_f32_e32 v86, v86
	s_waitcnt lgkmcnt(6)
	v_mfma_f32_32x32x16_bf16 v[16:31], v[132:135], v[164:167], v[16:31]
	ds_read_b128 v[128:131], v243 offset:62528
	ds_read_b128 v[132:135], v243 offset:62560
	v_exp_f32_e32 v87, v87
	v_exp_f32_e32 v88, v88
	v_exp_f32_e32 v89, v89
	s_waitcnt lgkmcnt(7)
	v_mfma_f32_32x32x16_bf16 v[0:15], v[136:139], v[160:163], v[0:15]
	v_exp_f32_e32 v90, v90
	v_exp_f32_e32 v91, v91
	v_exp_f32_e32 v92, v92
	s_waitcnt lgkmcnt(6)
	v_mfma_f32_32x32x16_bf16 v[0:15], v[140:143], v[164:167], v[0:15]
	ds_read_b128 v[136:139], v244 offset:13888
	ds_read_b128 v[140:143], v244 offset:13920
	v_exp_f32_e32 v93, v93
	v_exp_f32_e32 v94, v94
	v_exp_f32_e32 v95, v95
	s_waitcnt lgkmcnt(7)
	v_mfma_f32_32x32x16_bf16 v[48:63], v[144:147], v[160:163], v[48:63]
	v_cvt_pk_bf16_f32 v168, v80, v81
	v_cvt_pk_bf16_f32 v169, v82, v83
	s_waitcnt lgkmcnt(6)
	v_mfma_f32_32x32x16_bf16 v[48:63], v[148:151], v[164:167], v[48:63]
	ds_read_b128 v[144:147], v243 offset:53312
	ds_read_b128 v[148:151], v243 offset:53344
	v_cvt_pk_bf16_f32 v170, v84, v85
	v_cvt_pk_bf16_f32 v171, v86, v87
	s_waitcnt lgkmcnt(7)
	v_mfma_f32_32x32x16_bf16 v[32:47], v[152:155], v[160:163], v[32:47]
	v_cvt_pk_bf16_f32 v172, v88, v89
	v_cvt_pk_bf16_f32 v173, v90, v91
	s_waitcnt lgkmcnt(6)
	v_mfma_f32_32x32x16_bf16 v[32:47], v[156:159], v[164:167], v[32:47]
	ds_read_b128 v[152:155], v243 offset:57920
	ds_read_b128 v[156:159], v243 offset:57952
	v_cvt_pk_bf16_f32 v174, v92, v93
	v_cvt_pk_bf16_f32 v175, v94, v95
	s_nop 1
	s_waitcnt lgkmcnt(7)
	v_mfma_f32_32x32x16_bf16 v[16:31], v[128:131], v[168:171], v[16:31]
	s_cmp_eq_u64 s[40:41], 0
	s_cbranch_scc1 .La1t1n_lv_s
	s_waitcnt vmcnt(4)
	ds_write_b128 v239, v[96:99]
	ds_write_b128 v239, v[100:103] offset:8704
	ds_write2_b64 v241, v[120:121], v[122:123] offset1:2
	ds_write2_b64 v242, v[124:125], v[126:127] offset0:128 offset1:130

.La2t0_nl3:
	s_waitcnt lgkmcnt(7)
	v_mfma_f32_32x32x16_bf16 v[80:95], v[156:159], v[222:225], v[194:209]
	s_nop 11
	v_exp_f32_e32 v64, v64
	v_exp_f32_e32 v65, v65
	v_exp_f32_e32 v66, v66
	v_exp_f32_e32 v67, v67
	v_exp_f32_e32 v68, v68
	v_exp_f32_e32 v69, v69
	s_waitcnt lgkmcnt(6)
	v_mfma_f32_32x32x16_bf16 v[80:95], v[152:155], v[218:221], v[80:95]
	v_exp_f32_e32 v70, v70
	v_exp_f32_e32 v71, v71
	v_exp_f32_e32 v72, v72
	v_exp_f32_e32 v73, v73
	v_exp_f32_e32 v74, v74
	v_exp_f32_e32 v75, v75
	s_waitcnt lgkmcnt(5)
	v_mfma_f32_32x32x16_bf16 v[80:95], v[148:151], v[214:217], v[80:95]
	v_exp_f32_e32 v76, v76
	v_exp_f32_e32 v77, v77
	v_exp_f32_e32 v78, v78
	v_exp_f32_e32 v79, v79
	v_cvt_pk_bf16_f32 v160, v64, v65
	v_cvt_pk_bf16_f32 v161, v66, v67
	s_waitcnt lgkmcnt(4)
	v_mfma_f32_32x32x16_bf16 v[80:95], v[144:147], v[210:213], v[80:95]
	ds_read_b128 v[144:147], v243 offset:34816
	ds_read_b128 v[148:151], v243 offset:34848
	ds_read_b128 v[152:155], v243 offset:39424
	ds_read_b128 v[156:159], v243 offset:39456
	v_cvt_pk_bf16_f32 v162, v68, v69
	v_cvt_pk_bf16_f32 v163, v70, v71
	v_cvt_pk_bf16_f32 v164, v72, v73
	v_cvt_pk_bf16_f32 v165, v74, v75
	v_cvt_pk_bf16_f32 v166, v76, v77
	v_cvt_pk_bf16_f32 v167, v78, v79
	s_nop 4
	v_exp_f32_e32 v80, v80
	v_exp_f32_e32 v81, v81
	v_exp_f32_e32 v82, v82
	v_exp_f32_e32 v83, v83
	s_waitcnt lgkmcnt(7)
	v_mfma_f32_32x32x16_bf16 v[16:31], v[128:131], v[160:163], v[16:31]
	v_exp_f32_e32 v84, v84
	v_exp_f32_e32 v85, v85
	v_exp_f32_e32 v86, v86
	s_waitcnt lgkmcnt(6)
	v_mfma_f32_32x32x16_bf16 v[16:31], v[132:135], v[164:167], v[16:31]
	ds_read_b128 v[128:131], v243 offset:44096
	ds_read_b128 v[132:135], v243 offset:44128
	v_exp_f32_e32 v87, v87
	v_exp_f32_e32 v88, v88
	v_exp_f32_e32 v89, v89
	s_waitcnt lgkmcnt(7)
	v_mfma_f32_32x32x16_bf16 v[0:15], v[136:139], v[160:163], v[0:15]
	v_exp_f32_e32 v90, v90
	v_exp_f32_e32 v91, v91
	v_exp_f32_e32 v92, v92
	s_waitcnt lgkmcnt(6)
	v_mfma_f32_32x32x16_bf16 v[0:15], v[140:143], v[164:167], v[0:15]
	ds_read_b128 v[136:139], v243 offset:48704
	ds_read_b128 v[140:143], v243 offset:48736
	v_exp_f32_e32 v93, v93
	v_exp_f32_e32 v94, v94
	v_exp_f32_e32 v95, v95
	s_waitcnt lgkmcnt(7)
	v_mfma_f32_32x32x16_bf16 v[48:63], v[144:147], v[160:163], v[48:63]
	v_cvt_pk_bf16_f32 v168, v80, v81
	v_cvt_pk_bf16_f32 v169, v82, v83
	s_waitcnt lgkmcnt(6)
	v_mfma_f32_32x32x16_bf16 v[48:63], v[148:151], v[164:167], v[48:63]
	ds_read_b128 v[144:147], v243 offset:34880
	ds_read_b128 v[148:151], v243 offset:34912
	v_cvt_pk_bf16_f32 v170, v84, v85
	v_cvt_pk_bf16_f32 v171, v86, v87
	s_waitcnt lgkmcnt(7)
	v_mfma_f32_32x32x16_bf16 v[32:47], v[152:155], v[160:163], v[32:47]
	v_cvt_pk_bf16_f32 v172, v88, v89
	v_cvt_pk_bf16_f32 v173, v90, v91
	s_waitcnt lgkmcnt(6)
	v_mfma_f32_32x32x16_bf16 v[32:47], v[156:159], v[164:167], v[32:47]
	ds_read_b128 v[152:155], v243 offset:39488
	ds_read_b128 v[156:159], v243 offset:39520
	v_cvt_pk_bf16_f32 v174, v92, v93
	v_cvt_pk_bf16_f32 v175, v94, v95
	s_nop 1
	s_waitcnt lgkmcnt(7)
	v_mfma_f32_32x32x16_bf16 v[16:31], v[128:131], v[168:171], v[16:31]
	s_cmp_eq_u64 s[0:1], 0
	s_cbranch_scc1 .La2t0_lv_a
	s_waitcnt vmcnt(4)
	s_branch .La2t0_lv_b

.La2t0n_nl3:
	v_mfma_f32_32x32x16_bf16 v[80:95], v[156:159], v[222:225], v[80:95]
	s_nop 11
	v_exp_f32_e32 v64, v64
	v_exp_f32_e32 v65, v65
	v_exp_f32_e32 v66, v66
	v_exp_f32_e32 v67, v67
	v_exp_f32_e32 v68, v68
	v_exp_f32_e32 v69, v69
	v_mfma_f32_32x32x16_bf16 v[80:95], v[152:155], v[218:221], v[80:95]
	v_exp_f32_e32 v70, v70
	v_exp_f32_e32 v71, v71
	v_exp_f32_e32 v72, v72
	v_exp_f32_e32 v73, v73
	v_exp_f32_e32 v74, v74
	v_exp_f32_e32 v75, v75
	v_mfma_f32_32x32x16_bf16 v[80:95], v[148:151], v[214:217], v[80:95]
	v_exp_f32_e32 v76, v76
	v_exp_f32_e32 v77, v77
	v_exp_f32_e32 v78, v78
	v_exp_f32_e32 v79, v79
	v_cvt_pk_bf16_f32 v160, v64, v65
	v_cvt_pk_bf16_f32 v161, v66, v67
	v_mfma_f32_32x32x16_bf16 v[80:95], v[144:147], v[210:213], v[80:95]
	ds_read_b128 v[144:147], v243 offset:34816
	ds_read_b128 v[148:151], v243 offset:34848
	ds_read_b128 v[152:155], v243 offset:39424
	ds_read_b128 v[156:159], v243 offset:39456
	v_cvt_pk_bf16_f32 v162, v68, v69
	v_cvt_pk_bf16_f32 v163, v70, v71
	v_cvt_pk_bf16_f32 v164, v72, v73
	v_cvt_pk_bf16_f32 v165, v74, v75
	v_cvt_pk_bf16_f32 v166, v76, v77
	v_cvt_pk_bf16_f32 v167, v78, v79
	s_nop 4
	v_exp_f32_e32 v80, v80
	v_exp_f32_e32 v81, v81
	v_exp_f32_e32 v82, v82
	v_exp_f32_e32 v83, v83
	s_waitcnt lgkmcnt(7)
	v_mfma_f32_32x32x16_bf16 v[16:31], v[128:131], v[160:163], v[16:31]
	v_exp_f32_e32 v84, v84
	v_exp_f32_e32 v85, v85
	v_exp_f32_e32 v86, v86
	s_waitcnt lgkmcnt(6)
	v_mfma_f32_32x32x16_bf16 v[16:31], v[132:135], v[164:167], v[16:31]
	ds_read_b128 v[128:131], v243 offset:44096
	ds_read_b128 v[132:135], v243 offset:44128
	v_exp_f32_e32 v87, v87
	v_exp_f32_e32 v88, v88
	v_exp_f32_e32 v89, v89
	s_waitcnt lgkmcnt(7)
	v_mfma_f32_32x32x16_bf16 v[0:15], v[136:139], v[160:163], v[0:15]
	v_exp_f32_e32 v90, v90
	v_exp_f32_e32 v91, v91
	v_exp_f32_e32 v92, v92
	s_waitcnt lgkmcnt(6)
	v_mfma_f32_32x32x16_bf16 v[0:15], v[140:143], v[164:167], v[0:15]
	ds_read_b128 v[136:139], v243 offset:48704
	ds_read_b128 v[140:143], v243 offset:48736
	v_exp_f32_e32 v93, v93
	v_exp_f32_e32 v94, v94
	v_exp_f32_e32 v95, v95
	s_waitcnt lgkmcnt(7)
	v_mfma_f32_32x32x16_bf16 v[48:63], v[144:147], v[160:163], v[48:63]
	v_cvt_pk_bf16_f32 v168, v80, v81
	v_cvt_pk_bf16_f32 v169, v82, v83
	s_waitcnt lgkmcnt(6)
	v_mfma_f32_32x32x16_bf16 v[48:63], v[148:151], v[164:167], v[48:63]
	ds_read_b128 v[144:147], v243 offset:34880
	ds_read_b128 v[148:151], v243 offset:34912
	v_cvt_pk_bf16_f32 v170, v84, v85
	v_cvt_pk_bf16_f32 v171, v86, v87
	s_waitcnt lgkmcnt(7)
	v_mfma_f32_32x32x16_bf16 v[32:47], v[152:155], v[160:163], v[32:47]
	v_cvt_pk_bf16_f32 v172, v88, v89
	v_cvt_pk_bf16_f32 v173, v90, v91
	s_waitcnt lgkmcnt(6)
	v_mfma_f32_32x32x16_bf16 v[32:47], v[156:159], v[164:167], v[32:47]
	ds_read_b128 v[152:155], v243 offset:39488
	ds_read_b128 v[156:159], v243 offset:39520
	v_cvt_pk_bf16_f32 v174, v92, v93
	v_cvt_pk_bf16_f32 v175, v94, v95
	s_nop 1
	s_waitcnt lgkmcnt(7)
	v_mfma_f32_32x32x16_bf16 v[16:31], v[128:131], v[168:171], v[16:31]
	s_cmp_eq_u64 s[0:1], 0
	s_cbranch_scc1 .La2t0n_lv_a
	s_waitcnt vmcnt(4)
	s_branch .La2t0n_lv_b

.La2t1_nl3:
	s_waitcnt lgkmcnt(7)
	v_mfma_f32_32x32x16_bf16 v[80:95], v[156:159], v[222:225], v[194:209]
	s_nop 11
	v_exp_f32_e32 v64, v64
	v_exp_f32_e32 v65, v65
	v_exp_f32_e32 v66, v66
	v_exp_f32_e32 v67, v67
	v_exp_f32_e32 v68, v68
	v_exp_f32_e32 v69, v69
	s_waitcnt lgkmcnt(6)
	v_mfma_f32_32x32x16_bf16 v[80:95], v[152:155], v[218:221], v[80:95]
	v_exp_f32_e32 v70, v70
	v_exp_f32_e32 v71, v71
	v_exp_f32_e32 v72, v72
	v_exp_f32_e32 v73, v73
	v_exp_f32_e32 v74, v74
	v_exp_f32_e32 v75, v75
	s_waitcnt lgkmcnt(5)
	v_mfma_f32_32x32x16_bf16 v[80:95], v[148:151], v[214:217], v[80:95]
	v_exp_f32_e32 v76, v76
	v_exp_f32_e32 v77, v77
	v_exp_f32_e32 v78, v78
	v_exp_f32_e32 v79, v79
	v_cvt_pk_bf16_f32 v160, v64, v65
	v_cvt_pk_bf16_f32 v161, v66, v67
	s_waitcnt lgkmcnt(4)
	v_mfma_f32_32x32x16_bf16 v[80:95], v[144:147], v[210:213], v[80:95]
	ds_read_b128 v[144:147], v243 offset:53248
	ds_read_b128 v[148:151], v243 offset:53280
	ds_read_b128 v[152:155], v243 offset:57856
	ds_read_b128 v[156:159], v243 offset:57888
	v_cvt_pk_bf16_f32 v162, v68, v69
	v_cvt_pk_bf16_f32 v163, v70, v71
	v_cvt_pk_bf16_f32 v164, v72, v73
	v_cvt_pk_bf16_f32 v165, v74, v75
	v_cvt_pk_bf16_f32 v166, v76, v77
	v_cvt_pk_bf16_f32 v167, v78, v79
	s_nop 4
	v_exp_f32_e32 v80, v80
	v_exp_f32_e32 v81, v81
	v_exp_f32_e32 v82, v82
	v_exp_f32_e32 v83, v83
	s_waitcnt lgkmcnt(7)
	v_mfma_f32_32x32x16_bf16 v[16:31], v[128:131], v[160:163], v[16:31]
	v_exp_f32_e32 v84, v84
	v_exp_f32_e32 v85, v85
	v_exp_f32_e32 v86, v86
	s_waitcnt lgkmcnt(6)
	v_mfma_f32_32x32x16_bf16 v[16:31], v[132:135], v[164:167], v[16:31]
	ds_read_b128 v[128:131], v243 offset:62528
	ds_read_b128 v[132:135], v243 offset:62560
	v_exp_f32_e32 v87, v87
	v_exp_f32_e32 v88, v88
	v_exp_f32_e32 v89, v89
	s_waitcnt lgkmcnt(7)
	v_mfma_f32_32x32x16_bf16 v[0:15], v[136:139], v[160:163], v[0:15]
	v_exp_f32_e32 v90, v90
	v_exp_f32_e32 v91, v91
	v_exp_f32_e32 v92, v92
	s_waitcnt lgkmcnt(6)
	v_mfma_f32_32x32x16_bf16 v[0:15], v[140:143], v[164:167], v[0:15]
	ds_read_b128 v[136:139], v244 offset:13888
	ds_read_b128 v[140:143], v244 offset:13920
	v_exp_f32_e32 v93, v93
	v_exp_f32_e32 v94, v94
	v_exp_f32_e32 v95, v95
	s_waitcnt lgkmcnt(7)
	v_mfma_f32_32x32x16_bf16 v[48:63], v[144:147], v[160:163], v[48:63]
	v_cvt_pk_bf16_f32 v168, v80, v81
	v_cvt_pk_bf16_f32 v169, v82, v83
	s_waitcnt lgkmcnt(6)
	v_mfma_f32_32x32x16_bf16 v[48:63], v[148:151], v[164:167], v[48:63]
	ds_read_b128 v[144:147], v243 offset:53312
	ds_read_b128 v[148:151], v243 offset:53344
	v_cvt_pk_bf16_f32 v170, v84, v85
	v_cvt_pk_bf16_f32 v171, v86, v87
	s_waitcnt lgkmcnt(7)
	v_mfma_f32_32x32x16_bf16 v[32:47], v[152:155], v[160:163], v[32:47]
	v_cvt_pk_bf16_f32 v172, v88, v89
	v_cvt_pk_bf16_f32 v173, v90, v91
	s_waitcnt lgkmcnt(6)
	v_mfma_f32_32x32x16_bf16 v[32:47], v[156:159], v[164:167], v[32:47]
	ds_read_b128 v[152:155], v243 offset:57920
	ds_read_b128 v[156:159], v243 offset:57952
	v_cvt_pk_bf16_f32 v174, v92, v93
	v_cvt_pk_bf16_f32 v175, v94, v95
	s_nop 1
	s_waitcnt lgkmcnt(7)
	v_mfma_f32_32x32x16_bf16 v[16:31], v[128:131], v[168:171], v[16:31]
	s_cmp_eq_u64 s[0:1], 0
	s_cbranch_scc1 .La2t1_lv_s
	s_waitcnt vmcnt(4)
	ds_write_b128 v239, v[96:99]
	ds_write_b128 v239, v[100:103] offset:8704
	ds_write2_b64 v241, v[120:121], v[122:123] offset1:2
	ds_write2_b64 v242, v[124:125], v[126:127] offset0:128 offset1:130

.La2t1n_nl3:
	v_mfma_f32_32x32x16_bf16 v[80:95], v[156:159], v[222:225], v[80:95]
	s_nop 11
	v_exp_f32_e32 v64, v64
	v_exp_f32_e32 v65, v65
	v_exp_f32_e32 v66, v66
	v_exp_f32_e32 v67, v67
	v_exp_f32_e32 v68, v68
	v_exp_f32_e32 v69, v69
	v_mfma_f32_32x32x16_bf16 v[80:95], v[152:155], v[218:221], v[80:95]
	v_exp_f32_e32 v70, v70
	v_exp_f32_e32 v71, v71
	v_exp_f32_e32 v72, v72
	v_exp_f32_e32 v73, v73
	v_exp_f32_e32 v74, v74
	v_exp_f32_e32 v75, v75
	v_mfma_f32_32x32x16_bf16 v[80:95], v[148:151], v[214:217], v[80:95]
	v_exp_f32_e32 v76, v76
	v_exp_f32_e32 v77, v77
	v_exp_f32_e32 v78, v78
	v_exp_f32_e32 v79, v79
	v_cvt_pk_bf16_f32 v160, v64, v65
	v_cvt_pk_bf16_f32 v161, v66, v67
	v_mfma_f32_32x32x16_bf16 v[80:95], v[144:147], v[210:213], v[80:95]
	ds_read_b128 v[144:147], v243 offset:53248
	ds_read_b128 v[148:151], v243 offset:53280
	ds_read_b128 v[152:155], v243 offset:57856
	ds_read_b128 v[156:159], v243 offset:57888
	v_cvt_pk_bf16_f32 v162, v68, v69
	v_cvt_pk_bf16_f32 v163, v70, v71
	v_cvt_pk_bf16_f32 v164, v72, v73
	v_cvt_pk_bf16_f32 v165, v74, v75
	v_cvt_pk_bf16_f32 v166, v76, v77
	v_cvt_pk_bf16_f32 v167, v78, v79
	s_nop 4
	v_exp_f32_e32 v80, v80
	v_exp_f32_e32 v81, v81
	v_exp_f32_e32 v82, v82
	v_exp_f32_e32 v83, v83
	s_waitcnt lgkmcnt(7)
	v_mfma_f32_32x32x16_bf16 v[16:31], v[128:131], v[160:163], v[16:31]
	v_exp_f32_e32 v84, v84
	v_exp_f32_e32 v85, v85
	v_exp_f32_e32 v86, v86
	s_waitcnt lgkmcnt(6)
	v_mfma_f32_32x32x16_bf16 v[16:31], v[132:135], v[164:167], v[16:31]
	ds_read_b128 v[128:131], v243 offset:62528
	ds_read_b128 v[132:135], v243 offset:62560
	v_exp_f32_e32 v87, v87
	v_exp_f32_e32 v88, v88
	v_exp_f32_e32 v89, v89
	s_waitcnt lgkmcnt(7)
	v_mfma_f32_32x32x16_bf16 v[0:15], v[136:139], v[160:163], v[0:15]
	v_exp_f32_e32 v90, v90
	v_exp_f32_e32 v91, v91
	v_exp_f32_e32 v92, v92
	s_waitcnt lgkmcnt(6)
	v_mfma_f32_32x32x16_bf16 v[0:15], v[140:143], v[164:167], v[0:15]
	ds_read_b128 v[136:139], v244 offset:13888
	ds_read_b128 v[140:143], v244 offset:13920
	v_exp_f32_e32 v93, v93
	v_exp_f32_e32 v94, v94
	v_exp_f32_e32 v95, v95
	s_waitcnt lgkmcnt(7)
	v_mfma_f32_32x32x16_bf16 v[48:63], v[144:147], v[160:163], v[48:63]
	v_cvt_pk_bf16_f32 v168, v80, v81
	v_cvt_pk_bf16_f32 v169, v82, v83
	s_waitcnt lgkmcnt(6)
	v_mfma_f32_32x32x16_bf16 v[48:63], v[148:151], v[164:167], v[48:63]
	ds_read_b128 v[144:147], v243 offset:53312
	ds_read_b128 v[148:151], v243 offset:53344
	v_cvt_pk_bf16_f32 v170, v84, v85
	v_cvt_pk_bf16_f32 v171, v86, v87
	s_waitcnt lgkmcnt(7)
	v_mfma_f32_32x32x16_bf16 v[32:47], v[152:155], v[160:163], v[32:47]
	v_cvt_pk_bf16_f32 v172, v88, v89
	v_cvt_pk_bf16_f32 v173, v90, v91
	s_waitcnt lgkmcnt(6)
	v_mfma_f32_32x32x16_bf16 v[32:47], v[156:159], v[164:167], v[32:47]
	ds_read_b128 v[152:155], v243 offset:57920
	ds_read_b128 v[156:159], v243 offset:57952
	v_cvt_pk_bf16_f32 v174, v92, v93
	v_cvt_pk_bf16_f32 v175, v94, v95
	s_nop 1
	s_waitcnt lgkmcnt(7)
	v_mfma_f32_32x32x16_bf16 v[16:31], v[128:131], v[168:171], v[16:31]
	s_cmp_eq_u64 s[0:1], 0
	s_cbranch_scc1 .La2t1n_lv_s
	s_waitcnt vmcnt(4)
	ds_write_b128 v239, v[96:99]
	ds_write_b128 v239, v[100:103] offset:8704
	ds_write2_b64 v241, v[120:121], v[122:123] offset1:2
	ds_write2_b64 v242, v[124:125], v[126:127] offset0:128 offset1:130
